# v79 plus hand-written 16x16x32 tile for the QKV q/k column tiles: bias folded into the accumulator init, q scaled by QSCALE, fp16 copy as 16-byte stores, fp32 new_k rows as 16-byte stores
# speedup vs baseline: 1.0356x; 1.0059x over previous
.LBB0_301:
	s_andn2_saveexec_b64 s[50:51], s[50:51]
	s_cbranch_execz .LBB0_261
	s_waitcnt lgkmcnt(0)
	v_mfma_f32_32x32x16_f16 v[48:63], v[64:67], v[88:91], 0
	v_mfma_f32_32x32x16_f16 v[64:79], v[68:71], v[88:91], 0
	v_mfma_f32_32x32x16_f16 v[48:63], v[96:99], v[80:83], v[48:63]
	v_mfma_f32_32x32x16_f16 v[64:79], v[104:107], v[80:83], v[64:79]
	v_mfma_f32_32x32x16_f16 v[48:63], v[12:15], v[84:87], v[48:63]
	v_mfma_f32_32x32x16_f16 v[64:79], v[100:103], v[84:87], v[64:79]
	v_mfma_f32_32x32x16_f16 v[48:63], v[4:7], v[92:95], v[48:63]
	ds_read_b32 v4, v150 offset:16
	ds_read_b32 v5, v148 offset:16
	ds_read_b32 v6, v146 offset:16
	ds_read_b32 v7, v144 offset:16
	ds_read_b32 v12, v142 offset:16
	ds_read_b32 v13, v141 offset:16
	ds_read_b32 v97, v140 offset:16
	ds_read_b32 v98, v139 offset:16
	s_waitcnt lgkmcnt(0)
	s_nop 0
	v_add_f32_e32 v96, v48, v4
	v_mfma_f32_32x32x16_f16 v[64:79], v[8:11], v[92:95], v[64:79]
	ds_read_b32 v99, v149 offset:16
	ds_read_b32 v100, v147 offset:16
	ds_read_b32 v101, v145 offset:16
	ds_read_b32 v102, v143 offset:16
	ds_read_b32 v4, v138 offset:16
	ds_read_b32 v103, v137 offset:16
	ds_read_b32 v104, v136 offset:16
	ds_read_b32 v48, v135 offset:16
	s_nop 1
	v_add_f32_e32 v69, v49, v5
	s_waitcnt lgkmcnt(0)
	v_add_f32_e32 v11, v56, v4
	v_add_f32_e32 v15, v52, v12
	v_add_f32_e32 v14, v53, v13
	v_add_f32_e32 v68, v65, v100
	v_add_f32_e32 v65, v50, v6
	v_add_f32_e32 v50, v51, v7
	ds_read_b32 v4, v134 offset:16
	ds_read_b32 v5, v133 offset:16
	ds_read_b32 v51, v132 offset:16
	ds_read_b32 v0, v131 offset:16
	v_add_f32_e32 v70, v64, v99
	s_waitcnt lgkmcnt(0)
	v_add_f32_e32 v7, v60, v4
	v_add_f32_e32 v64, v66, v101
	v_add_f32_e32 v49, v67, v102
	v_add_f32_e32 v4, v63, v0
	v_max3_f32 v0, v96, s55, v70
	v_max3_f32 v0, v0, v69, v68
	v_max3_f32 v0, v0, v65, v64
	v_max3_f32 v0, v0, v50, v49
	v_add_f32_e32 v13, v54, v97
	v_add_f32_e32 v12, v55, v98
	v_max3_f32 v0, v0, v15, v14
	v_add_f32_e32 v10, v57, v103
	v_max3_f32 v0, v0, v13, v12
	v_add_f32_e32 v9, v58, v104
	v_add_f32_e32 v8, v59, v48
	v_max3_f32 v0, v0, v11, v10
	v_add_f32_e32 v6, v61, v5
	v_max3_f32 v0, v0, v9, v8
	v_add_f32_e32 v5, v62, v51
	v_max3_f32 v0, v0, v7, v6
	v_max3_f32 v0, v0, v5, v4
	v_mov_b32_e32 v48, v0
	s_nop 1
	v_permlane32_swap_b32_e32 v0, v48
	v_max3_f32 v48, v186, v0, v48
	v_sub_f32_e32 v0, v186, v48
	v_exp_f32_e32 v0, v0
	s_nop 0
	v_cmp_neq_f32_e32 vcc, 1.0, v0
	s_cbranch_vccz .LBB0_260
	v_mul_f32_e32 v30, v0, v30
	v_mul_f32_e32 v31, v0, v31
	v_mul_f32_e32 v28, v0, v28
	v_mul_f32_e32 v29, v0, v29
	v_mul_f32_e32 v26, v0, v26
	v_mul_f32_e32 v27, v0, v27
	v_mul_f32_e32 v24, v0, v24
	v_mul_f32_e32 v25, v0, v25
	v_mul_f32_e32 v22, v0, v22
	v_mul_f32_e32 v23, v0, v23
	v_mul_f32_e32 v20, v0, v20
	v_mul_f32_e32 v21, v0, v21
	v_mul_f32_e32 v18, v0, v18
	v_mul_f32_e32 v19, v0, v19
	v_mul_f32_e32 v16, v0, v16
	v_mul_f32_e32 v17, v0, v17
	v_mul_f32_e32 v46, v0, v46
	v_mul_f32_e32 v47, v0, v47
	v_mul_f32_e32 v44, v0, v44
	v_mul_f32_e32 v45, v0, v45
	v_mul_f32_e32 v42, v0, v42
	v_mul_f32_e32 v43, v0, v43
	v_mul_f32_e32 v40, v0, v40
	v_mul_f32_e32 v41, v0, v41
	v_mul_f32_e32 v38, v0, v38
	v_mul_f32_e32 v39, v0, v39
	v_mul_f32_e32 v36, v0, v36
	v_mul_f32_e32 v37, v0, v37
	v_mul_f32_e32 v34, v0, v34
	v_mul_f32_e32 v35, v0, v35
	v_mul_f32_e32 v32, v0, v32
	v_mul_f32_e32 v33, v0, v33
	s_branch .LBB0_260
.LBB0_305:
	v_readlane_b32 s24, v234, 0
	s_add_i32 s82, s82, s24
	v_readlane_b32 s24, v236, 17
	s_cmp_ge_i32 s82, s24
	v_readlane_b32 s83, v235, 60
	s_cbranch_scc1 .LBB0_653

.LBB0_448:
	s_load_dwordx2 s[30:31], s[22:23], 0xe8
	s_lshl_b32 s46, s48, 8
	s_lshl_b32 s45, s83, 11
	s_add_u32 s24, s62, s45
	s_addc_u32 s25, s63, 0
	s_lshl_b32 s45, s46, 11
	s_add_u32 s28, s64, s45
	s_addc_u32 s29, s65, 0
	s_waitcnt lgkmcnt(0)
	v_readfirstlane_b32 s45, v200
	s_lshr_b32 s45, s45, 6
	s_lshl_b32 s32, s45, 11
	s_add_u32 s32, s32, 16
	s_lshl_b32 s45, s45, 16
	s_add_u32 s24, s24, s45
	s_addc_u32 s25, s25, 0
	s_add_u32 s28, s28, s45
	s_addc_u32 s29, s29, 0
	v_bfe_u32 v173, v200, 4, 2
	v_sub_u32_e32 v173, 0, v173
	v_and_b32_e32 v173, 3, v173
	v_and_b32_e32 v172, 3, v200
	v_xor_b32_e32 v172, v172, v173
	v_bfe_u32 v173, v200, 2, 4
	v_lshlrev_b32_e32 v173, 11, v173
	v_lshl_or_b32 v170, v172, 4, v173
	v_add_u32_e32 v171, 0x8000, v170
	v_bfe_u32 v172, v200, 2, 2
	v_sub_u32_e32 v172, 0, v172
	v_and_b32_e32 v172, 3, v172
	v_bfe_u32 v173, v200, 4, 2
	v_xor_b32_e32 v172, v172, v173
	v_and_b32_e32 v173, 15, v200
	v_bfe_u32 v174, v200, 8, 1
	v_lshl_or_b32 v174, v174, 7, v173
	v_lshlrev_b32_e32 v174, 6, v174
	v_lshl_or_b32 v164, v172, 4, v174
	v_bfe_u32 v174, v200, 6, 2
	v_lshl_or_b32 v174, v174, 6, v173
	v_lshlrev_b32_e32 v174, 6, v174
	v_lshl_or_b32 v165, v172, 4, v174
	v_add_u32_e32 v165, 0x4000, v165
	v_bfe_u32 v172, v200, 6, 2
	v_bfe_u32 v173, v200, 4, 2
	v_lshlrev_b32_e32 v172, 6, v172
	v_lshl_or_b32 v172, v173, 2, v172
	v_add_u32_e32 v172, s46, v172
	v_lshlrev_b32_e32 v172, 2, v172
	global_load_dwordx4 v[132:135], v172, s[30:31]
	global_load_dwordx4 v[136:139], v172, s[30:31] offset:64
	global_load_dwordx4 v[140:143], v172, s[30:31] offset:128
	global_load_dwordx4 v[144:147], v172, s[30:31] offset:192
	s_mov_b32 s43, s32
	s_mov_b32 m0, s43
	s_nop 0
	global_load_lds_dwordx4 v170, s[24:25]
	s_add_u32 m0, s43, 0x400
	s_nop 0
	global_load_lds_dwordx4 v171, s[24:25]
	s_add_u32 m0, s43, 0x4000
	s_nop 0
	global_load_lds_dwordx4 v170, s[28:29]
	s_add_u32 m0, s43, 0x4400
	s_nop 0
	global_load_lds_dwordx4 v171, s[28:29]
	s_add_u32 s24, s24, 64
	s_addc_u32 s25, s25, 0
	s_add_u32 s28, s28, 64
	s_addc_u32 s29, s29, 0
	s_add_u32 s43, s32, 0x8000
	s_mov_b32 m0, s43
	s_nop 0
	global_load_lds_dwordx4 v170, s[24:25]
	s_add_u32 m0, s43, 0x400
	s_nop 0
	global_load_lds_dwordx4 v171, s[24:25]
	s_add_u32 m0, s43, 0x4000
	s_nop 0
	global_load_lds_dwordx4 v170, s[28:29]
	s_add_u32 m0, s43, 0x4400
	s_nop 0
	global_load_lds_dwordx4 v171, s[28:29]
	s_add_u32 s24, s24, 64
	s_addc_u32 s25, s25, 0
	s_add_u32 s28, s28, 64
	s_addc_u32 s29, s29, 0
	s_add_u32 s43, s32, 0x10000
	s_mov_b32 m0, s43
	s_nop 0
	global_load_lds_dwordx4 v170, s[24:25]
	s_add_u32 m0, s43, 0x400
	s_nop 0
	global_load_lds_dwordx4 v171, s[24:25]
	s_add_u32 m0, s43, 0x4000
	s_nop 0
	global_load_lds_dwordx4 v170, s[28:29]
	s_add_u32 m0, s43, 0x4400
	s_nop 0
	global_load_lds_dwordx4 v171, s[28:29]
	s_add_u32 s24, s24, 64
	s_addc_u32 s25, s25, 0
	s_add_u32 s28, s28, 64
	s_addc_u32 s29, s29, 0
	s_add_u32 s43, s32, 0x18000
	s_mov_b32 m0, s43
	s_nop 0
	global_load_lds_dwordx4 v170, s[24:25]
	s_add_u32 m0, s43, 0x400
	s_nop 0
	global_load_lds_dwordx4 v171, s[24:25]
	s_add_u32 m0, s43, 0x4000
	s_nop 0
	global_load_lds_dwordx4 v170, s[28:29]
	s_add_u32 m0, s43, 0x4400
	s_nop 0
	global_load_lds_dwordx4 v171, s[28:29]
	s_add_u32 s24, s24, 64
	s_addc_u32 s25, s25, 0
	s_add_u32 s28, s28, 64
	s_addc_u32 s29, s29, 0
	s_waitcnt vmcnt(16)
	v_mov_b32_e32 v4, v132
	v_mov_b32_e32 v5, v133
	v_mov_b32_e32 v6, v134
	v_mov_b32_e32 v7, v135
	v_mov_b32_e32 v8, v136
	v_mov_b32_e32 v9, v137
	v_mov_b32_e32 v10, v138
	v_mov_b32_e32 v11, v139
	v_mov_b32_e32 v12, v140
	v_mov_b32_e32 v13, v141
	v_mov_b32_e32 v14, v142
	v_mov_b32_e32 v15, v143
	v_mov_b32_e32 v16, v144
	v_mov_b32_e32 v17, v145
	v_mov_b32_e32 v18, v146
	v_mov_b32_e32 v19, v147
	v_mov_b32_e32 v20, v132
	v_mov_b32_e32 v21, v133
	v_mov_b32_e32 v22, v134
	v_mov_b32_e32 v23, v135
	v_mov_b32_e32 v24, v136
	v_mov_b32_e32 v25, v137
	v_mov_b32_e32 v26, v138
	v_mov_b32_e32 v27, v139
	v_mov_b32_e32 v28, v140
	v_mov_b32_e32 v29, v141
	v_mov_b32_e32 v30, v142
	v_mov_b32_e32 v31, v143
	v_mov_b32_e32 v32, v144
	v_mov_b32_e32 v33, v145
	v_mov_b32_e32 v34, v146
	v_mov_b32_e32 v35, v147
	v_mov_b32_e32 v36, v132
	v_mov_b32_e32 v37, v133
	v_mov_b32_e32 v38, v134
	v_mov_b32_e32 v39, v135
	v_mov_b32_e32 v40, v136
	v_mov_b32_e32 v41, v137
	v_mov_b32_e32 v42, v138
	v_mov_b32_e32 v43, v139
	v_mov_b32_e32 v44, v140
	v_mov_b32_e32 v45, v141
	v_mov_b32_e32 v46, v142
	v_mov_b32_e32 v47, v143
	v_mov_b32_e32 v48, v144
	v_mov_b32_e32 v49, v145
	v_mov_b32_e32 v50, v146
	v_mov_b32_e32 v51, v147
	v_mov_b32_e32 v52, v132
	v_mov_b32_e32 v53, v133
	v_mov_b32_e32 v54, v134
	v_mov_b32_e32 v55, v135
	v_mov_b32_e32 v56, v136
	v_mov_b32_e32 v57, v137
	v_mov_b32_e32 v58, v138
	v_mov_b32_e32 v59, v139
	v_mov_b32_e32 v60, v140
	v_mov_b32_e32 v61, v141
	v_mov_b32_e32 v62, v142
	v_mov_b32_e32 v63, v143
	v_mov_b32_e32 v64, v144
	v_mov_b32_e32 v65, v145
	v_mov_b32_e32 v66, v146
	v_mov_b32_e32 v67, v147
	v_mov_b32_e32 v68, v132
	v_mov_b32_e32 v69, v133
	v_mov_b32_e32 v70, v134
	v_mov_b32_e32 v71, v135
	v_mov_b32_e32 v72, v136
	v_mov_b32_e32 v73, v137
	v_mov_b32_e32 v74, v138
	v_mov_b32_e32 v75, v139
	v_mov_b32_e32 v76, v140
	v_mov_b32_e32 v77, v141
	v_mov_b32_e32 v78, v142
	v_mov_b32_e32 v79, v143
	v_mov_b32_e32 v80, v144
	v_mov_b32_e32 v81, v145
	v_mov_b32_e32 v82, v146
	v_mov_b32_e32 v83, v147
	v_mov_b32_e32 v84, v132
	v_mov_b32_e32 v85, v133
	v_mov_b32_e32 v86, v134
	v_mov_b32_e32 v87, v135
	v_mov_b32_e32 v88, v136
	v_mov_b32_e32 v89, v137
	v_mov_b32_e32 v90, v138
	v_mov_b32_e32 v91, v139
	v_mov_b32_e32 v92, v140
	v_mov_b32_e32 v93, v141
	v_mov_b32_e32 v94, v142
	v_mov_b32_e32 v95, v143
	v_mov_b32_e32 v96, v144
	v_mov_b32_e32 v97, v145
	v_mov_b32_e32 v98, v146
	v_mov_b32_e32 v99, v147
	v_mov_b32_e32 v100, v132
	v_mov_b32_e32 v101, v133
	v_mov_b32_e32 v102, v134
	v_mov_b32_e32 v103, v135
	v_mov_b32_e32 v104, v136
	v_mov_b32_e32 v105, v137
	v_mov_b32_e32 v106, v138
	v_mov_b32_e32 v107, v139
	v_mov_b32_e32 v108, v140
	v_mov_b32_e32 v109, v141
	v_mov_b32_e32 v110, v142
	v_mov_b32_e32 v111, v143
	v_mov_b32_e32 v112, v144
	v_mov_b32_e32 v113, v145
	v_mov_b32_e32 v114, v146
	v_mov_b32_e32 v115, v147
	v_mov_b32_e32 v116, v132
	v_mov_b32_e32 v117, v133
	v_mov_b32_e32 v118, v134
	v_mov_b32_e32 v119, v135
	v_mov_b32_e32 v120, v136
	v_mov_b32_e32 v121, v137
	v_mov_b32_e32 v122, v138
	v_mov_b32_e32 v123, v139
	v_mov_b32_e32 v124, v140
	v_mov_b32_e32 v125, v141
	v_mov_b32_e32 v126, v142
	v_mov_b32_e32 v127, v143
	v_mov_b32_e32 v128, v144
	v_mov_b32_e32 v129, v145
	v_mov_b32_e32 v130, v146
	v_mov_b32_e32 v131, v147
	s_waitcnt vmcnt(12)
	s_barrier
	s_mov_b32 s42, 0
	s_mov_b32 s44, 0
	s_nop 1
	v_add_u32_e32 v168, s42, v165
	v_add_u32_e32 v169, s42, v164
	ds_read_b128 v[132:135], v168 offset:16
	ds_read_b128 v[136:139], v168 offset:1040
	ds_read_b128 v[140:143], v168 offset:2064
	ds_read_b128 v[144:147], v168 offset:3088
	ds_read_b128 v[184:187], v169 offset:16
	ds_read_b128 v[188:191], v169 offset:1040
	ds_read_b128 v[192:195], v169 offset:2064
	ds_read_b128 v[196:199], v169 offset:3088
	s_waitcnt lgkmcnt(0)
.Lt_qkv_qk:
	v_add_u32_e32 v169, s42, v164
	v_mfma_f32_16x16x32_f16 v[4:7], v[132:135], v[184:187], v[4:7]
	ds_read_b128 v[238:241], v169 offset:4112
	v_mfma_f32_16x16x32_f16 v[8:11], v[136:139], v[184:187], v[8:11]
	ds_read_b128 v[242:245], v169 offset:5136
	v_mfma_f32_16x16x32_f16 v[12:15], v[140:143], v[184:187], v[12:15]
	ds_read_b128 v[246:249], v169 offset:6160
	v_mfma_f32_16x16x32_f16 v[16:19], v[144:147], v[184:187], v[16:19]
	ds_read_b128 v[250:253], v169 offset:7184
	v_mfma_f32_16x16x32_f16 v[20:23], v[132:135], v[188:191], v[20:23]
	v_mfma_f32_16x16x32_f16 v[24:27], v[136:139], v[188:191], v[24:27]
	v_mfma_f32_16x16x32_f16 v[28:31], v[140:143], v[188:191], v[28:31]
	v_mfma_f32_16x16x32_f16 v[32:35], v[144:147], v[188:191], v[32:35]
	v_mfma_f32_16x16x32_f16 v[36:39], v[132:135], v[192:195], v[36:39]
	v_mfma_f32_16x16x32_f16 v[40:43], v[136:139], v[192:195], v[40:43]
	v_mfma_f32_16x16x32_f16 v[44:47], v[140:143], v[192:195], v[44:47]
	v_mfma_f32_16x16x32_f16 v[48:51], v[144:147], v[192:195], v[48:51]
	v_mfma_f32_16x16x32_f16 v[52:55], v[132:135], v[196:199], v[52:55]
	v_mfma_f32_16x16x32_f16 v[56:59], v[136:139], v[196:199], v[56:59]
	v_mfma_f32_16x16x32_f16 v[60:63], v[140:143], v[196:199], v[60:63]
	v_mfma_f32_16x16x32_f16 v[64:67], v[144:147], v[196:199], v[64:67]
	s_waitcnt vmcnt(8) lgkmcnt(0)
	s_barrier
	s_add_i32 s43, s42, 0x8000
	s_cmp_lg_u32 s42, 0x18000
	s_cselect_b32 s43, s43, 0
	v_add_u32_e32 v168, s43, v165
	v_add_u32_e32 v169, s43, v164
	s_add_u32 vcc_lo, s32, s42
	v_mfma_f32_16x16x32_f16 v[68:71], v[132:135], v[238:241], v[68:71]
	ds_read_b128 v[148:151], v168 offset:16
	ds_read_b128 v[184:187], v169 offset:16
	v_mfma_f32_16x16x32_f16 v[72:75], v[136:139], v[238:241], v[72:75]
	ds_read_b128 v[152:155], v168 offset:1040
	ds_read_b128 v[188:191], v169 offset:1040
	v_mfma_f32_16x16x32_f16 v[76:79], v[140:143], v[238:241], v[76:79]
	ds_read_b128 v[156:159], v168 offset:2064
	ds_read_b128 v[192:195], v169 offset:2064
	v_mfma_f32_16x16x32_f16 v[80:83], v[144:147], v[238:241], v[80:83]
	ds_read_b128 v[160:163], v168 offset:3088
	ds_read_b128 v[196:199], v169 offset:3088
	v_mfma_f32_16x16x32_f16 v[84:87], v[132:135], v[242:245], v[84:87]
	v_mfma_f32_16x16x32_f16 v[88:91], v[136:139], v[242:245], v[88:91]
	v_mfma_f32_16x16x32_f16 v[92:95], v[140:143], v[242:245], v[92:95]
	v_mfma_f32_16x16x32_f16 v[96:99], v[144:147], v[242:245], v[96:99]
	v_mfma_f32_16x16x32_f16 v[100:103], v[132:135], v[246:249], v[100:103]
	s_mov_b32 m0, vcc_lo
	s_nop 0
	global_load_lds_dwordx4 v170, s[24:25]
	v_mfma_f32_16x16x32_f16 v[104:107], v[136:139], v[246:249], v[104:107]
	s_add_u32 m0, vcc_lo, 0x400
	s_nop 0
	global_load_lds_dwordx4 v171, s[24:25]
	v_mfma_f32_16x16x32_f16 v[108:111], v[140:143], v[246:249], v[108:111]
	s_add_u32 m0, vcc_lo, 0x4000
	s_nop 0
	global_load_lds_dwordx4 v170, s[28:29]
	v_mfma_f32_16x16x32_f16 v[112:115], v[144:147], v[246:249], v[112:115]
	s_add_u32 m0, vcc_lo, 0x4400
	s_nop 0
	global_load_lds_dwordx4 v171, s[28:29]
	v_mfma_f32_16x16x32_f16 v[116:119], v[132:135], v[250:253], v[116:119]
	v_mfma_f32_16x16x32_f16 v[120:123], v[136:139], v[250:253], v[120:123]
	v_mfma_f32_16x16x32_f16 v[124:127], v[140:143], v[250:253], v[124:127]
	v_mfma_f32_16x16x32_f16 v[128:131], v[144:147], v[250:253], v[128:131]
	s_waitcnt lgkmcnt(0)
	s_mov_b32 s42, s43
	s_add_u32 s24, s24, 64
	s_addc_u32 s25, s25, 0
	s_add_u32 s28, s28, 64
	s_addc_u32 s29, s29, 0
	v_add_u32_e32 v169, s42, v164
	v_mfma_f32_16x16x32_f16 v[4:7], v[148:151], v[184:187], v[4:7]
	ds_read_b128 v[238:241], v169 offset:4112
	v_mfma_f32_16x16x32_f16 v[8:11], v[152:155], v[184:187], v[8:11]
	ds_read_b128 v[242:245], v169 offset:5136
	v_mfma_f32_16x16x32_f16 v[12:15], v[156:159], v[184:187], v[12:15]
	ds_read_b128 v[246:249], v169 offset:6160
	v_mfma_f32_16x16x32_f16 v[16:19], v[160:163], v[184:187], v[16:19]
	ds_read_b128 v[250:253], v169 offset:7184
	v_mfma_f32_16x16x32_f16 v[20:23], v[148:151], v[188:191], v[20:23]
	v_mfma_f32_16x16x32_f16 v[24:27], v[152:155], v[188:191], v[24:27]
	v_mfma_f32_16x16x32_f16 v[28:31], v[156:159], v[188:191], v[28:31]
	v_mfma_f32_16x16x32_f16 v[32:35], v[160:163], v[188:191], v[32:35]
	v_mfma_f32_16x16x32_f16 v[36:39], v[148:151], v[192:195], v[36:39]
	v_mfma_f32_16x16x32_f16 v[40:43], v[152:155], v[192:195], v[40:43]
	v_mfma_f32_16x16x32_f16 v[44:47], v[156:159], v[192:195], v[44:47]
	v_mfma_f32_16x16x32_f16 v[48:51], v[160:163], v[192:195], v[48:51]
	v_mfma_f32_16x16x32_f16 v[52:55], v[148:151], v[196:199], v[52:55]
	v_mfma_f32_16x16x32_f16 v[56:59], v[152:155], v[196:199], v[56:59]
	v_mfma_f32_16x16x32_f16 v[60:63], v[156:159], v[196:199], v[60:63]
	v_mfma_f32_16x16x32_f16 v[64:67], v[160:163], v[196:199], v[64:67]
	s_waitcnt vmcnt(8) lgkmcnt(0)
	s_barrier
	s_add_i32 s43, s42, 0x8000
	s_cmp_lg_u32 s42, 0x18000
	s_cselect_b32 s43, s43, 0
	v_add_u32_e32 v168, s43, v165
	v_add_u32_e32 v169, s43, v164
	s_add_u32 vcc_lo, s32, s42
	v_mfma_f32_16x16x32_f16 v[68:71], v[148:151], v[238:241], v[68:71]
	ds_read_b128 v[132:135], v168 offset:16
	ds_read_b128 v[184:187], v169 offset:16
	v_mfma_f32_16x16x32_f16 v[72:75], v[152:155], v[238:241], v[72:75]
	ds_read_b128 v[136:139], v168 offset:1040
	ds_read_b128 v[188:191], v169 offset:1040
	v_mfma_f32_16x16x32_f16 v[76:79], v[156:159], v[238:241], v[76:79]
	ds_read_b128 v[140:143], v168 offset:2064
	ds_read_b128 v[192:195], v169 offset:2064
	v_mfma_f32_16x16x32_f16 v[80:83], v[160:163], v[238:241], v[80:83]
	ds_read_b128 v[144:147], v168 offset:3088
	ds_read_b128 v[196:199], v169 offset:3088
	v_mfma_f32_16x16x32_f16 v[84:87], v[148:151], v[242:245], v[84:87]
	v_mfma_f32_16x16x32_f16 v[88:91], v[152:155], v[242:245], v[88:91]
	v_mfma_f32_16x16x32_f16 v[92:95], v[156:159], v[242:245], v[92:95]
	v_mfma_f32_16x16x32_f16 v[96:99], v[160:163], v[242:245], v[96:99]
	v_mfma_f32_16x16x32_f16 v[100:103], v[148:151], v[246:249], v[100:103]
	s_mov_b32 m0, vcc_lo
	s_nop 0
	global_load_lds_dwordx4 v170, s[24:25]
	v_mfma_f32_16x16x32_f16 v[104:107], v[152:155], v[246:249], v[104:107]
	s_add_u32 m0, vcc_lo, 0x400
	s_nop 0
	global_load_lds_dwordx4 v171, s[24:25]
	v_mfma_f32_16x16x32_f16 v[108:111], v[156:159], v[246:249], v[108:111]
	s_add_u32 m0, vcc_lo, 0x4000
	s_nop 0
	global_load_lds_dwordx4 v170, s[28:29]
	v_mfma_f32_16x16x32_f16 v[112:115], v[160:163], v[246:249], v[112:115]
	s_add_u32 m0, vcc_lo, 0x4400
	s_nop 0
	global_load_lds_dwordx4 v171, s[28:29]
	v_mfma_f32_16x16x32_f16 v[116:119], v[148:151], v[250:253], v[116:119]
	v_mfma_f32_16x16x32_f16 v[120:123], v[152:155], v[250:253], v[120:123]
	v_mfma_f32_16x16x32_f16 v[124:127], v[156:159], v[250:253], v[124:127]
	v_mfma_f32_16x16x32_f16 v[128:131], v[160:163], v[250:253], v[128:131]
	s_waitcnt lgkmcnt(0)
	s_mov_b32 s42, s43
	s_add_u32 s24, s24, 64
	s_addc_u32 s25, s25, 0
	s_add_u32 s28, s28, 64
	s_addc_u32 s29, s29, 0
	s_add_i32 s44, s44, 2
	s_cmp_lt_u32 s44, 28
	s_cbranch_scc1 .Lt_qkv_qk
	v_add_u32_e32 v169, s42, v164
	v_mfma_f32_16x16x32_f16 v[4:7], v[132:135], v[184:187], v[4:7]
	ds_read_b128 v[238:241], v169 offset:4112
	v_mfma_f32_16x16x32_f16 v[8:11], v[136:139], v[184:187], v[8:11]
	ds_read_b128 v[242:245], v169 offset:5136
	v_mfma_f32_16x16x32_f16 v[12:15], v[140:143], v[184:187], v[12:15]
	ds_read_b128 v[246:249], v169 offset:6160
	v_mfma_f32_16x16x32_f16 v[16:19], v[144:147], v[184:187], v[16:19]
	ds_read_b128 v[250:253], v169 offset:7184
	v_mfma_f32_16x16x32_f16 v[20:23], v[132:135], v[188:191], v[20:23]
	v_mfma_f32_16x16x32_f16 v[24:27], v[136:139], v[188:191], v[24:27]
	v_mfma_f32_16x16x32_f16 v[28:31], v[140:143], v[188:191], v[28:31]
	v_mfma_f32_16x16x32_f16 v[32:35], v[144:147], v[188:191], v[32:35]
	v_mfma_f32_16x16x32_f16 v[36:39], v[132:135], v[192:195], v[36:39]
	v_mfma_f32_16x16x32_f16 v[40:43], v[136:139], v[192:195], v[40:43]
	v_mfma_f32_16x16x32_f16 v[44:47], v[140:143], v[192:195], v[44:47]
	v_mfma_f32_16x16x32_f16 v[48:51], v[144:147], v[192:195], v[48:51]
	v_mfma_f32_16x16x32_f16 v[52:55], v[132:135], v[196:199], v[52:55]
	v_mfma_f32_16x16x32_f16 v[56:59], v[136:139], v[196:199], v[56:59]
	v_mfma_f32_16x16x32_f16 v[60:63], v[140:143], v[196:199], v[60:63]
	v_mfma_f32_16x16x32_f16 v[64:67], v[144:147], v[196:199], v[64:67]
	s_waitcnt vmcnt(8) lgkmcnt(0)
	s_barrier
	s_add_i32 s43, s42, 0x8000
	s_cmp_lg_u32 s42, 0x18000
	s_cselect_b32 s43, s43, 0
	v_add_u32_e32 v168, s43, v165
	v_add_u32_e32 v169, s43, v164
	v_mfma_f32_16x16x32_f16 v[68:71], v[132:135], v[238:241], v[68:71]
	ds_read_b128 v[148:151], v168 offset:16
	ds_read_b128 v[184:187], v169 offset:16
	v_mfma_f32_16x16x32_f16 v[72:75], v[136:139], v[238:241], v[72:75]
	ds_read_b128 v[152:155], v168 offset:1040
	ds_read_b128 v[188:191], v169 offset:1040
	v_mfma_f32_16x16x32_f16 v[76:79], v[140:143], v[238:241], v[76:79]
	ds_read_b128 v[156:159], v168 offset:2064
	ds_read_b128 v[192:195], v169 offset:2064
	v_mfma_f32_16x16x32_f16 v[80:83], v[144:147], v[238:241], v[80:83]
	ds_read_b128 v[160:163], v168 offset:3088
	ds_read_b128 v[196:199], v169 offset:3088
	v_mfma_f32_16x16x32_f16 v[84:87], v[132:135], v[242:245], v[84:87]
	v_mfma_f32_16x16x32_f16 v[88:91], v[136:139], v[242:245], v[88:91]
	v_mfma_f32_16x16x32_f16 v[92:95], v[140:143], v[242:245], v[92:95]
	v_mfma_f32_16x16x32_f16 v[96:99], v[144:147], v[242:245], v[96:99]
	v_mfma_f32_16x16x32_f16 v[100:103], v[132:135], v[246:249], v[100:103]
	v_mfma_f32_16x16x32_f16 v[104:107], v[136:139], v[246:249], v[104:107]
	v_mfma_f32_16x16x32_f16 v[108:111], v[140:143], v[246:249], v[108:111]
	v_mfma_f32_16x16x32_f16 v[112:115], v[144:147], v[246:249], v[112:115]
	v_mfma_f32_16x16x32_f16 v[116:119], v[132:135], v[250:253], v[116:119]
	v_mfma_f32_16x16x32_f16 v[120:123], v[136:139], v[250:253], v[120:123]
	v_mfma_f32_16x16x32_f16 v[124:127], v[140:143], v[250:253], v[124:127]
	v_mfma_f32_16x16x32_f16 v[128:131], v[144:147], v[250:253], v[128:131]
	s_waitcnt lgkmcnt(0)
	s_mov_b32 s42, s43
	v_add_u32_e32 v169, s42, v164
	v_mfma_f32_16x16x32_f16 v[4:7], v[148:151], v[184:187], v[4:7]
	ds_read_b128 v[238:241], v169 offset:4112
	v_mfma_f32_16x16x32_f16 v[8:11], v[152:155], v[184:187], v[8:11]
	ds_read_b128 v[242:245], v169 offset:5136
	v_mfma_f32_16x16x32_f16 v[12:15], v[156:159], v[184:187], v[12:15]
	ds_read_b128 v[246:249], v169 offset:6160
	v_mfma_f32_16x16x32_f16 v[16:19], v[160:163], v[184:187], v[16:19]
	ds_read_b128 v[250:253], v169 offset:7184
	v_mfma_f32_16x16x32_f16 v[20:23], v[148:151], v[188:191], v[20:23]
	v_mfma_f32_16x16x32_f16 v[24:27], v[152:155], v[188:191], v[24:27]
	v_mfma_f32_16x16x32_f16 v[28:31], v[156:159], v[188:191], v[28:31]
	v_mfma_f32_16x16x32_f16 v[32:35], v[160:163], v[188:191], v[32:35]
	v_mfma_f32_16x16x32_f16 v[36:39], v[148:151], v[192:195], v[36:39]
	v_mfma_f32_16x16x32_f16 v[40:43], v[152:155], v[192:195], v[40:43]
	v_mfma_f32_16x16x32_f16 v[44:47], v[156:159], v[192:195], v[44:47]
	v_mfma_f32_16x16x32_f16 v[48:51], v[160:163], v[192:195], v[48:51]
	v_mfma_f32_16x16x32_f16 v[52:55], v[148:151], v[196:199], v[52:55]
	v_mfma_f32_16x16x32_f16 v[56:59], v[152:155], v[196:199], v[56:59]
	v_mfma_f32_16x16x32_f16 v[60:63], v[156:159], v[196:199], v[60:63]
	v_mfma_f32_16x16x32_f16 v[64:67], v[160:163], v[196:199], v[64:67]
	s_waitcnt vmcnt(4) lgkmcnt(0)
	s_barrier
	s_add_i32 s43, s42, 0x8000
	s_cmp_lg_u32 s42, 0x18000
	s_cselect_b32 s43, s43, 0
	v_add_u32_e32 v168, s43, v165
	v_add_u32_e32 v169, s43, v164
	v_mfma_f32_16x16x32_f16 v[68:71], v[148:151], v[238:241], v[68:71]
	ds_read_b128 v[132:135], v168 offset:16
	ds_read_b128 v[184:187], v169 offset:16
	v_mfma_f32_16x16x32_f16 v[72:75], v[152:155], v[238:241], v[72:75]
	ds_read_b128 v[136:139], v168 offset:1040
	ds_read_b128 v[188:191], v169 offset:1040
	v_mfma_f32_16x16x32_f16 v[76:79], v[156:159], v[238:241], v[76:79]
	ds_read_b128 v[140:143], v168 offset:2064
	ds_read_b128 v[192:195], v169 offset:2064
	v_mfma_f32_16x16x32_f16 v[80:83], v[160:163], v[238:241], v[80:83]
	ds_read_b128 v[144:147], v168 offset:3088
	ds_read_b128 v[196:199], v169 offset:3088
	v_mfma_f32_16x16x32_f16 v[84:87], v[148:151], v[242:245], v[84:87]
	v_mfma_f32_16x16x32_f16 v[88:91], v[152:155], v[242:245], v[88:91]
	v_mfma_f32_16x16x32_f16 v[92:95], v[156:159], v[242:245], v[92:95]
	v_mfma_f32_16x16x32_f16 v[96:99], v[160:163], v[242:245], v[96:99]
	v_mfma_f32_16x16x32_f16 v[100:103], v[148:151], v[246:249], v[100:103]
	v_mfma_f32_16x16x32_f16 v[104:107], v[152:155], v[246:249], v[104:107]
	v_mfma_f32_16x16x32_f16 v[108:111], v[156:159], v[246:249], v[108:111]
	v_mfma_f32_16x16x32_f16 v[112:115], v[160:163], v[246:249], v[112:115]
	v_mfma_f32_16x16x32_f16 v[116:119], v[148:151], v[250:253], v[116:119]
	v_mfma_f32_16x16x32_f16 v[120:123], v[152:155], v[250:253], v[120:123]
	v_mfma_f32_16x16x32_f16 v[124:127], v[156:159], v[250:253], v[124:127]
	v_mfma_f32_16x16x32_f16 v[128:131], v[160:163], v[250:253], v[128:131]
	s_waitcnt lgkmcnt(0)
	s_mov_b32 s42, s43
	v_add_u32_e32 v169, s42, v164
	v_mfma_f32_16x16x32_f16 v[4:7], v[132:135], v[184:187], v[4:7]
	ds_read_b128 v[238:241], v169 offset:4112
	v_mfma_f32_16x16x32_f16 v[8:11], v[136:139], v[184:187], v[8:11]
	ds_read_b128 v[242:245], v169 offset:5136
	v_mfma_f32_16x16x32_f16 v[12:15], v[140:143], v[184:187], v[12:15]
	ds_read_b128 v[246:249], v169 offset:6160
	v_mfma_f32_16x16x32_f16 v[16:19], v[144:147], v[184:187], v[16:19]
	ds_read_b128 v[250:253], v169 offset:7184
	v_mfma_f32_16x16x32_f16 v[20:23], v[132:135], v[188:191], v[20:23]
	v_mfma_f32_16x16x32_f16 v[24:27], v[136:139], v[188:191], v[24:27]
	v_mfma_f32_16x16x32_f16 v[28:31], v[140:143], v[188:191], v[28:31]
	v_mfma_f32_16x16x32_f16 v[32:35], v[144:147], v[188:191], v[32:35]
	v_mfma_f32_16x16x32_f16 v[36:39], v[132:135], v[192:195], v[36:39]
	v_mfma_f32_16x16x32_f16 v[40:43], v[136:139], v[192:195], v[40:43]
	v_mfma_f32_16x16x32_f16 v[44:47], v[140:143], v[192:195], v[44:47]
	v_mfma_f32_16x16x32_f16 v[48:51], v[144:147], v[192:195], v[48:51]
	v_mfma_f32_16x16x32_f16 v[52:55], v[132:135], v[196:199], v[52:55]
	v_mfma_f32_16x16x32_f16 v[56:59], v[136:139], v[196:199], v[56:59]
	v_mfma_f32_16x16x32_f16 v[60:63], v[140:143], v[196:199], v[60:63]
	v_mfma_f32_16x16x32_f16 v[64:67], v[144:147], v[196:199], v[64:67]
	s_waitcnt vmcnt(0) lgkmcnt(0)
	s_barrier
	s_add_i32 s43, s42, 0x8000
	s_cmp_lg_u32 s42, 0x18000
	s_cselect_b32 s43, s43, 0
	v_add_u32_e32 v168, s43, v165
	v_add_u32_e32 v169, s43, v164
	v_mfma_f32_16x16x32_f16 v[68:71], v[132:135], v[238:241], v[68:71]
	ds_read_b128 v[148:151], v168 offset:16
	ds_read_b128 v[184:187], v169 offset:16
	v_mfma_f32_16x16x32_f16 v[72:75], v[136:139], v[238:241], v[72:75]
	ds_read_b128 v[152:155], v168 offset:1040
	ds_read_b128 v[188:191], v169 offset:1040
	v_mfma_f32_16x16x32_f16 v[76:79], v[140:143], v[238:241], v[76:79]
	ds_read_b128 v[156:159], v168 offset:2064
	ds_read_b128 v[192:195], v169 offset:2064
	v_mfma_f32_16x16x32_f16 v[80:83], v[144:147], v[238:241], v[80:83]
	ds_read_b128 v[160:163], v168 offset:3088
	ds_read_b128 v[196:199], v169 offset:3088
	v_mfma_f32_16x16x32_f16 v[84:87], v[132:135], v[242:245], v[84:87]
	v_mfma_f32_16x16x32_f16 v[88:91], v[136:139], v[242:245], v[88:91]
	v_mfma_f32_16x16x32_f16 v[92:95], v[140:143], v[242:245], v[92:95]
	v_mfma_f32_16x16x32_f16 v[96:99], v[144:147], v[242:245], v[96:99]
	v_mfma_f32_16x16x32_f16 v[100:103], v[132:135], v[246:249], v[100:103]
	v_mfma_f32_16x16x32_f16 v[104:107], v[136:139], v[246:249], v[104:107]
	v_mfma_f32_16x16x32_f16 v[108:111], v[140:143], v[246:249], v[108:111]
	v_mfma_f32_16x16x32_f16 v[112:115], v[144:147], v[246:249], v[112:115]
	v_mfma_f32_16x16x32_f16 v[116:119], v[132:135], v[250:253], v[116:119]
	v_mfma_f32_16x16x32_f16 v[120:123], v[136:139], v[250:253], v[120:123]
	v_mfma_f32_16x16x32_f16 v[124:127], v[140:143], v[250:253], v[124:127]
	v_mfma_f32_16x16x32_f16 v[128:131], v[144:147], v[250:253], v[128:131]
	s_waitcnt lgkmcnt(0)
	s_mov_b32 s42, s43
	v_add_u32_e32 v169, s42, v164
	v_mfma_f32_16x16x32_f16 v[4:7], v[148:151], v[184:187], v[4:7]
	ds_read_b128 v[238:241], v169 offset:4112
	v_mfma_f32_16x16x32_f16 v[8:11], v[152:155], v[184:187], v[8:11]
	ds_read_b128 v[242:245], v169 offset:5136
	v_mfma_f32_16x16x32_f16 v[12:15], v[156:159], v[184:187], v[12:15]
	ds_read_b128 v[246:249], v169 offset:6160
	v_mfma_f32_16x16x32_f16 v[16:19], v[160:163], v[184:187], v[16:19]
	ds_read_b128 v[250:253], v169 offset:7184
	v_mfma_f32_16x16x32_f16 v[20:23], v[148:151], v[188:191], v[20:23]
	v_mfma_f32_16x16x32_f16 v[24:27], v[152:155], v[188:191], v[24:27]
	v_mfma_f32_16x16x32_f16 v[28:31], v[156:159], v[188:191], v[28:31]
	v_mfma_f32_16x16x32_f16 v[32:35], v[160:163], v[188:191], v[32:35]
	v_mfma_f32_16x16x32_f16 v[36:39], v[148:151], v[192:195], v[36:39]
	v_mfma_f32_16x16x32_f16 v[40:43], v[152:155], v[192:195], v[40:43]
	v_mfma_f32_16x16x32_f16 v[44:47], v[156:159], v[192:195], v[44:47]
	v_mfma_f32_16x16x32_f16 v[48:51], v[160:163], v[192:195], v[48:51]
	v_mfma_f32_16x16x32_f16 v[52:55], v[148:151], v[196:199], v[52:55]
	v_mfma_f32_16x16x32_f16 v[56:59], v[152:155], v[196:199], v[56:59]
	v_mfma_f32_16x16x32_f16 v[60:63], v[156:159], v[196:199], v[60:63]
	v_mfma_f32_16x16x32_f16 v[64:67], v[160:163], v[196:199], v[64:67]
	s_waitcnt lgkmcnt(0)
	s_barrier
	v_mfma_f32_16x16x32_f16 v[68:71], v[148:151], v[238:241], v[68:71]
	v_mfma_f32_16x16x32_f16 v[72:75], v[152:155], v[238:241], v[72:75]
	v_mfma_f32_16x16x32_f16 v[76:79], v[156:159], v[238:241], v[76:79]
	v_mfma_f32_16x16x32_f16 v[80:83], v[160:163], v[238:241], v[80:83]
	v_mfma_f32_16x16x32_f16 v[84:87], v[148:151], v[242:245], v[84:87]
	v_mfma_f32_16x16x32_f16 v[88:91], v[152:155], v[242:245], v[88:91]
	v_mfma_f32_16x16x32_f16 v[92:95], v[156:159], v[242:245], v[92:95]
	v_mfma_f32_16x16x32_f16 v[96:99], v[160:163], v[242:245], v[96:99]
	v_mfma_f32_16x16x32_f16 v[100:103], v[148:151], v[246:249], v[100:103]
	v_mfma_f32_16x16x32_f16 v[104:107], v[152:155], v[246:249], v[104:107]
	v_mfma_f32_16x16x32_f16 v[108:111], v[156:159], v[246:249], v[108:111]
	v_mfma_f32_16x16x32_f16 v[112:115], v[160:163], v[246:249], v[112:115]
	v_mfma_f32_16x16x32_f16 v[116:119], v[148:151], v[250:253], v[116:119]
	v_mfma_f32_16x16x32_f16 v[120:123], v[152:155], v[250:253], v[120:123]
	v_mfma_f32_16x16x32_f16 v[124:127], v[156:159], v[250:253], v[124:127]
	v_mfma_f32_16x16x32_f16 v[128:131], v[160:163], v[250:253], v[128:131]
	s_and_b32 s32, s48, 3
	s_lshl_b32 s32, s32, 9
	s_lshl_b32 s42, s83, 11
	s_add_u32 s32, s32, s42
	s_cmp_lt_u32 s48, 4
	s_cselect_b32 s42, 0, 0x2800000
	s_add_u32 s32, s32, s42
	s_add_u32 s24, s80, s32
	s_addc_u32 s25, s81, 0
	v_and_b32_e32 v172, 15, v200
	v_bfe_u32 v173, v200, 4, 2
	v_bfe_u32 v174, v200, 6, 2
	v_bfe_u32 v175, v200, 8, 1
	v_lshl_or_b32 v175, v175, 7, v172
	v_lshlrev_b32_e32 v176, 16, v174
	v_lshl_add_u32 v176, v175, 8, v176
	v_lshl_add_u32 v176, v173, 4, v176
	v_lshlrev_b32_e32 v177, 11, v175
	v_lshl_or_b32 v174, v174, 4, v173
	v_lshl_add_u32 v177, v174, 3, v177
	v_and_b32_e32 v172, 1, v173
	v_mul_u32_u24_e32 v172, 24, v172
	v_add_u32_e32 v177, v177, v172
	s_cmp_lt_u32 s48, 4
	s_cbranch_scc0 .Lqk_k
	v_pk_mul_f32 v[4:5], v[4:5], s[12:13] op_sel_hi:[1,0]
	v_pk_mul_f32 v[6:7], v[6:7], s[12:13] op_sel_hi:[1,0]
	v_pk_mul_f32 v[8:9], v[8:9], s[12:13] op_sel_hi:[1,0]
	v_pk_mul_f32 v[10:11], v[10:11], s[12:13] op_sel_hi:[1,0]
	v_pk_mul_f32 v[12:13], v[12:13], s[12:13] op_sel_hi:[1,0]
	v_pk_mul_f32 v[14:15], v[14:15], s[12:13] op_sel_hi:[1,0]
	v_pk_mul_f32 v[16:17], v[16:17], s[12:13] op_sel_hi:[1,0]
	v_pk_mul_f32 v[18:19], v[18:19], s[12:13] op_sel_hi:[1,0]
	v_pk_mul_f32 v[20:21], v[20:21], s[12:13] op_sel_hi:[1,0]
	v_pk_mul_f32 v[22:23], v[22:23], s[12:13] op_sel_hi:[1,0]
	v_pk_mul_f32 v[24:25], v[24:25], s[12:13] op_sel_hi:[1,0]
	v_pk_mul_f32 v[26:27], v[26:27], s[12:13] op_sel_hi:[1,0]
	v_pk_mul_f32 v[28:29], v[28:29], s[12:13] op_sel_hi:[1,0]
	v_pk_mul_f32 v[30:31], v[30:31], s[12:13] op_sel_hi:[1,0]
	v_pk_mul_f32 v[32:33], v[32:33], s[12:13] op_sel_hi:[1,0]
	v_pk_mul_f32 v[34:35], v[34:35], s[12:13] op_sel_hi:[1,0]
	v_pk_mul_f32 v[36:37], v[36:37], s[12:13] op_sel_hi:[1,0]
	v_pk_mul_f32 v[38:39], v[38:39], s[12:13] op_sel_hi:[1,0]
	v_pk_mul_f32 v[40:41], v[40:41], s[12:13] op_sel_hi:[1,0]
	v_pk_mul_f32 v[42:43], v[42:43], s[12:13] op_sel_hi:[1,0]
	v_pk_mul_f32 v[44:45], v[44:45], s[12:13] op_sel_hi:[1,0]
	v_pk_mul_f32 v[46:47], v[46:47], s[12:13] op_sel_hi:[1,0]
	v_pk_mul_f32 v[48:49], v[48:49], s[12:13] op_sel_hi:[1,0]
	v_pk_mul_f32 v[50:51], v[50:51], s[12:13] op_sel_hi:[1,0]
	v_pk_mul_f32 v[52:53], v[52:53], s[12:13] op_sel_hi:[1,0]
	v_pk_mul_f32 v[54:55], v[54:55], s[12:13] op_sel_hi:[1,0]
	v_pk_mul_f32 v[56:57], v[56:57], s[12:13] op_sel_hi:[1,0]
	v_pk_mul_f32 v[58:59], v[58:59], s[12:13] op_sel_hi:[1,0]
	v_pk_mul_f32 v[60:61], v[60:61], s[12:13] op_sel_hi:[1,0]
	v_pk_mul_f32 v[62:63], v[62:63], s[12:13] op_sel_hi:[1,0]
	v_pk_mul_f32 v[64:65], v[64:65], s[12:13] op_sel_hi:[1,0]
	v_pk_mul_f32 v[66:67], v[66:67], s[12:13] op_sel_hi:[1,0]
	v_pk_mul_f32 v[68:69], v[68:69], s[12:13] op_sel_hi:[1,0]
	v_pk_mul_f32 v[70:71], v[70:71], s[12:13] op_sel_hi:[1,0]
	v_pk_mul_f32 v[72:73], v[72:73], s[12:13] op_sel_hi:[1,0]
	v_pk_mul_f32 v[74:75], v[74:75], s[12:13] op_sel_hi:[1,0]
	v_pk_mul_f32 v[76:77], v[76:77], s[12:13] op_sel_hi:[1,0]
	v_pk_mul_f32 v[78:79], v[78:79], s[12:13] op_sel_hi:[1,0]
	v_pk_mul_f32 v[80:81], v[80:81], s[12:13] op_sel_hi:[1,0]
	v_pk_mul_f32 v[82:83], v[82:83], s[12:13] op_sel_hi:[1,0]
	v_pk_mul_f32 v[84:85], v[84:85], s[12:13] op_sel_hi:[1,0]
	v_pk_mul_f32 v[86:87], v[86:87], s[12:13] op_sel_hi:[1,0]
	v_pk_mul_f32 v[88:89], v[88:89], s[12:13] op_sel_hi:[1,0]
	v_pk_mul_f32 v[90:91], v[90:91], s[12:13] op_sel_hi:[1,0]
	v_pk_mul_f32 v[92:93], v[92:93], s[12:13] op_sel_hi:[1,0]
	v_pk_mul_f32 v[94:95], v[94:95], s[12:13] op_sel_hi:[1,0]
	v_pk_mul_f32 v[96:97], v[96:97], s[12:13] op_sel_hi:[1,0]
	v_pk_mul_f32 v[98:99], v[98:99], s[12:13] op_sel_hi:[1,0]
	v_pk_mul_f32 v[100:101], v[100:101], s[12:13] op_sel_hi:[1,0]
	v_pk_mul_f32 v[102:103], v[102:103], s[12:13] op_sel_hi:[1,0]
	v_pk_mul_f32 v[104:105], v[104:105], s[12:13] op_sel_hi:[1,0]
	v_pk_mul_f32 v[106:107], v[106:107], s[12:13] op_sel_hi:[1,0]
	v_pk_mul_f32 v[108:109], v[108:109], s[12:13] op_sel_hi:[1,0]
	v_pk_mul_f32 v[110:111], v[110:111], s[12:13] op_sel_hi:[1,0]
	v_pk_mul_f32 v[112:113], v[112:113], s[12:13] op_sel_hi:[1,0]
	v_pk_mul_f32 v[114:115], v[114:115], s[12:13] op_sel_hi:[1,0]
	v_pk_mul_f32 v[116:117], v[116:117], s[12:13] op_sel_hi:[1,0]
	v_pk_mul_f32 v[118:119], v[118:119], s[12:13] op_sel_hi:[1,0]
	v_pk_mul_f32 v[120:121], v[120:121], s[12:13] op_sel_hi:[1,0]
	v_pk_mul_f32 v[122:123], v[122:123], s[12:13] op_sel_hi:[1,0]
	v_pk_mul_f32 v[124:125], v[124:125], s[12:13] op_sel_hi:[1,0]
	v_pk_mul_f32 v[126:127], v[126:127], s[12:13] op_sel_hi:[1,0]
	v_pk_mul_f32 v[128:129], v[128:129], s[12:13] op_sel_hi:[1,0]
	v_pk_mul_f32 v[130:131], v[130:131], s[12:13] op_sel_hi:[1,0]
	s_branch .Lqk_pack
.Lqk_k:
	s_cmp_lt_u32 s83, 0x1000
	s_cbranch_scc0 .Lqk_pack
	s_lshr_b32 s32, s83, 4
	s_sub_i32 s42, s48, 4
	s_lshl_b32 s42, s42, 2
	s_add_u32 s32, s32, s42
	s_lshl_b32 s32, s32, 16
	s_add_u32 s28, s72, s32
	s_addc_u32 s29, s73, 0
	global_store_dwordx4 v176, v[4:7], s[28:29]
	global_store_dwordx4 v176, v[8:11], s[28:29] offset:64
	global_store_dwordx4 v176, v[12:15], s[28:29] offset:128
	global_store_dwordx4 v176, v[16:19], s[28:29] offset:192
	v_add_u32_e32 v176, 0x1000, v176
	global_store_dwordx4 v176, v[20:23], s[28:29]
	global_store_dwordx4 v176, v[24:27], s[28:29] offset:64
	global_store_dwordx4 v176, v[28:31], s[28:29] offset:128
	global_store_dwordx4 v176, v[32:35], s[28:29] offset:192
	v_add_u32_e32 v176, 0x1000, v176
	global_store_dwordx4 v176, v[36:39], s[28:29]
	global_store_dwordx4 v176, v[40:43], s[28:29] offset:64
	global_store_dwordx4 v176, v[44:47], s[28:29] offset:128
	global_store_dwordx4 v176, v[48:51], s[28:29] offset:192
	v_add_u32_e32 v176, 0x1000, v176
	global_store_dwordx4 v176, v[52:55], s[28:29]
	global_store_dwordx4 v176, v[56:59], s[28:29] offset:64
	global_store_dwordx4 v176, v[60:63], s[28:29] offset:128
	global_store_dwordx4 v176, v[64:67], s[28:29] offset:192
	v_add_u32_e32 v176, 0x1000, v176
	global_store_dwordx4 v176, v[68:71], s[28:29]
	global_store_dwordx4 v176, v[72:75], s[28:29] offset:64
	global_store_dwordx4 v176, v[76:79], s[28:29] offset:128
	global_store_dwordx4 v176, v[80:83], s[28:29] offset:192
	v_add_u32_e32 v176, 0x1000, v176
	global_store_dwordx4 v176, v[84:87], s[28:29]
	global_store_dwordx4 v176, v[88:91], s[28:29] offset:64
	global_store_dwordx4 v176, v[92:95], s[28:29] offset:128
	global_store_dwordx4 v176, v[96:99], s[28:29] offset:192
	v_add_u32_e32 v176, 0x1000, v176
	global_store_dwordx4 v176, v[100:103], s[28:29]
	global_store_dwordx4 v176, v[104:107], s[28:29] offset:64
	global_store_dwordx4 v176, v[108:111], s[28:29] offset:128
	global_store_dwordx4 v176, v[112:115], s[28:29] offset:192
	v_add_u32_e32 v176, 0x1000, v176
	global_store_dwordx4 v176, v[116:119], s[28:29]
	global_store_dwordx4 v176, v[120:123], s[28:29] offset:64
	global_store_dwordx4 v176, v[124:127], s[28:29] offset:128
	global_store_dwordx4 v176, v[128:131], s[28:29] offset:192
.Lqk_pack:
	v_cvt_pk_f16_f32 v172, v4, v5
	v_cvt_pk_f16_f32 v173, v6, v7
	v_cvt_pk_f16_f32 v174, v8, v9
	v_cvt_pk_f16_f32 v175, v10, v11
	s_nop 1
	v_permlane16_swap_b32_e32 v172, v174
	v_permlane16_swap_b32_e32 v173, v175
	global_store_dwordx4 v177, v[172:175], s[24:25]
	v_cvt_pk_f16_f32 v228, v12, v13
	v_cvt_pk_f16_f32 v229, v14, v15
	v_cvt_pk_f16_f32 v230, v16, v17
	v_cvt_pk_f16_f32 v231, v18, v19
	s_nop 1
	v_permlane16_swap_b32_e32 v228, v230
	v_permlane16_swap_b32_e32 v229, v231
	global_store_dwordx4 v177, v[228:231], s[24:25] offset:64
	v_add_u32_e32 v177, 0x8000, v177
	v_cvt_pk_f16_f32 v172, v20, v21
	v_cvt_pk_f16_f32 v173, v22, v23
	v_cvt_pk_f16_f32 v174, v24, v25
	v_cvt_pk_f16_f32 v175, v26, v27
	s_nop 1
	v_permlane16_swap_b32_e32 v172, v174
	v_permlane16_swap_b32_e32 v173, v175
	global_store_dwordx4 v177, v[172:175], s[24:25]
	v_cvt_pk_f16_f32 v228, v28, v29
	v_cvt_pk_f16_f32 v229, v30, v31
	v_cvt_pk_f16_f32 v230, v32, v33
	v_cvt_pk_f16_f32 v231, v34, v35
	s_nop 1
	v_permlane16_swap_b32_e32 v228, v230
	v_permlane16_swap_b32_e32 v229, v231
	global_store_dwordx4 v177, v[228:231], s[24:25] offset:64
	v_add_u32_e32 v177, 0x8000, v177
	v_cvt_pk_f16_f32 v172, v36, v37
	v_cvt_pk_f16_f32 v173, v38, v39
	v_cvt_pk_f16_f32 v174, v40, v41
	v_cvt_pk_f16_f32 v175, v42, v43
	s_nop 1
	v_permlane16_swap_b32_e32 v172, v174
	v_permlane16_swap_b32_e32 v173, v175
	global_store_dwordx4 v177, v[172:175], s[24:25]
	v_cvt_pk_f16_f32 v228, v44, v45
	v_cvt_pk_f16_f32 v229, v46, v47
	v_cvt_pk_f16_f32 v230, v48, v49
	v_cvt_pk_f16_f32 v231, v50, v51
	s_nop 1
	v_permlane16_swap_b32_e32 v228, v230
	v_permlane16_swap_b32_e32 v229, v231
	global_store_dwordx4 v177, v[228:231], s[24:25] offset:64
	v_add_u32_e32 v177, 0x8000, v177
	v_cvt_pk_f16_f32 v172, v52, v53
	v_cvt_pk_f16_f32 v173, v54, v55
	v_cvt_pk_f16_f32 v174, v56, v57
	v_cvt_pk_f16_f32 v175, v58, v59
	s_nop 1
	v_permlane16_swap_b32_e32 v172, v174
	v_permlane16_swap_b32_e32 v173, v175
	global_store_dwordx4 v177, v[172:175], s[24:25]
	v_cvt_pk_f16_f32 v228, v60, v61
	v_cvt_pk_f16_f32 v229, v62, v63
	v_cvt_pk_f16_f32 v230, v64, v65
	v_cvt_pk_f16_f32 v231, v66, v67
	s_nop 1
	v_permlane16_swap_b32_e32 v228, v230
	v_permlane16_swap_b32_e32 v229, v231
	global_store_dwordx4 v177, v[228:231], s[24:25] offset:64
	v_add_u32_e32 v177, 0x8000, v177
	v_cvt_pk_f16_f32 v172, v68, v69
	v_cvt_pk_f16_f32 v173, v70, v71
	v_cvt_pk_f16_f32 v174, v72, v73
	v_cvt_pk_f16_f32 v175, v74, v75
	s_nop 1
	v_permlane16_swap_b32_e32 v172, v174
	v_permlane16_swap_b32_e32 v173, v175
	global_store_dwordx4 v177, v[172:175], s[24:25]
	v_cvt_pk_f16_f32 v228, v76, v77
	v_cvt_pk_f16_f32 v229, v78, v79
	v_cvt_pk_f16_f32 v230, v80, v81
	v_cvt_pk_f16_f32 v231, v82, v83
	s_nop 1
	v_permlane16_swap_b32_e32 v228, v230
	v_permlane16_swap_b32_e32 v229, v231
	global_store_dwordx4 v177, v[228:231], s[24:25] offset:64
	v_add_u32_e32 v177, 0x8000, v177
	v_cvt_pk_f16_f32 v172, v84, v85
	v_cvt_pk_f16_f32 v173, v86, v87
	v_cvt_pk_f16_f32 v174, v88, v89
	v_cvt_pk_f16_f32 v175, v90, v91
	s_nop 1
	v_permlane16_swap_b32_e32 v172, v174
	v_permlane16_swap_b32_e32 v173, v175
	global_store_dwordx4 v177, v[172:175], s[24:25]
	v_cvt_pk_f16_f32 v228, v92, v93
	v_cvt_pk_f16_f32 v229, v94, v95
	v_cvt_pk_f16_f32 v230, v96, v97
	v_cvt_pk_f16_f32 v231, v98, v99
	s_nop 1
	v_permlane16_swap_b32_e32 v228, v230
	v_permlane16_swap_b32_e32 v229, v231
	global_store_dwordx4 v177, v[228:231], s[24:25] offset:64
	v_add_u32_e32 v177, 0x8000, v177
	v_cvt_pk_f16_f32 v172, v100, v101
	v_cvt_pk_f16_f32 v173, v102, v103
	v_cvt_pk_f16_f32 v174, v104, v105
	v_cvt_pk_f16_f32 v175, v106, v107
	s_nop 1
	v_permlane16_swap_b32_e32 v172, v174
	v_permlane16_swap_b32_e32 v173, v175
	global_store_dwordx4 v177, v[172:175], s[24:25]
	v_cvt_pk_f16_f32 v228, v108, v109
	v_cvt_pk_f16_f32 v229, v110, v111
	v_cvt_pk_f16_f32 v230, v112, v113
	v_cvt_pk_f16_f32 v231, v114, v115
	s_nop 1
	v_permlane16_swap_b32_e32 v228, v230
	v_permlane16_swap_b32_e32 v229, v231
	global_store_dwordx4 v177, v[228:231], s[24:25] offset:64
	v_add_u32_e32 v177, 0x8000, v177
	v_cvt_pk_f16_f32 v172, v116, v117
	v_cvt_pk_f16_f32 v173, v118, v119
	v_cvt_pk_f16_f32 v174, v120, v121
	v_cvt_pk_f16_f32 v175, v122, v123
	s_nop 1
	v_permlane16_swap_b32_e32 v172, v174
	v_permlane16_swap_b32_e32 v173, v175
	global_store_dwordx4 v177, v[172:175], s[24:25]
	v_cvt_pk_f16_f32 v228, v124, v125
	v_cvt_pk_f16_f32 v229, v126, v127
	v_cvt_pk_f16_f32 v230, v128, v129
	v_cvt_pk_f16_f32 v231, v130, v131
	s_nop 1
	v_permlane16_swap_b32_e32 v228, v230
	v_permlane16_swap_b32_e32 v229, v231
	global_store_dwordx4 v177, v[228:231], s[24:25] offset:64
	s_nop 1
	s_branch .LBB0_305
